# attention with K/V rows staged in LDS once per workgroup (LDS-DMA, double buffered, one barrier per key row) + split-K out-projection, hoisted row loads, batched scan LDS reads, GEMM loop at offset 24
# baseline (speedup 1.0000x reference)
; #define LAS __attribute__((address_space(3)))
; #define LDS_WAIT() asm volatile("s_waitcnt lgkmcnt(0)" ::: "memory")
; __device__ __forceinline__ void attn_phase(const Args& a, int layer, LAS unsigned char* lds, int G, int need_ctx) {
;     const int tid = my_tid(), wave = __builtin_amdgcn_readfirstlane(tid >> 6), lane = tid & 63, q = lane & 31, hh = lane >> 5;
;     const bf16_t* Q = (const bf16_t*)(a.ws + WS_S0); const bf16_t* Kp = (const bf16_t*)(a.ws + WS_S0 + SLOT);
;     const bf16_t* SZ = (const bf16_t*)(a.ws + WS_S0 + 2 * SLOT); const bf16_t* Vt = (const bf16_t*)(a.ws + WS_S0 + 3 * SLOT);
;     bf16_t* GT = (bf16_t*)(a.ws + WS_S0 + 4 * SLOT);
;     const float* rpb = a.in[9] + (size_t)(layer / 3) * 32 * 465;
;     LAS float* rp = (LAS float*)(lds + wave * 2048);
;     const int gw = blockIdx.x * NWAVES + wave, NGW = G * NWAVES;
;     const int nlat = 8192, ntask = nlat + (need_ctx ? 1024 : 0);
;     const int sig = (q & 19) | ((q & 8) >> 1) | ((q & 4) << 1);
;     for (int task = gw; task < ntask; task += NGW) {
;         const bool lat = task < nlat;
;         int b, h, r = 0, j = 0, qtok;
;         if (lat) { j = task & 3; r = 2 * ((task >> 2) & 15); h = (task >> 6) & 31; b = task >> 11; qtok = b * SEQ + (r + (q >> 4)) * 64 + 16 * j + (q & 15); }
;         else { const int t2 = task - nlat; h = (t2 >> 3) & 31; b = t2 >> 8; qtok = MLAT + b * CTX + 32 * (t2 & 7) + q; }
;         bf16x8 qf[8];
; #pragma unroll
;         for (int c = 0; c < 8; ++c) qf[c] = *(const bf16x8*)(Q + (size_t)qtok * DI + h * 128 + 16 * c + 8 * hh);
;         if (lat) {
;             LDS_WAIT();
;             for (int e = lane; e < 465; e += 64) rp[e] = rpb[h * 465 + e];
;             LDS_WAIT();
;         }
;         const int r0a = min(max(r - 4, 0), 24), r0b = min(max(r - 3, 0), 24), nband = lat ? (r0b + 8 - r0a) : 0;
;         const int qr = r + (q >> 4), myr0 = (q >> 4) ? r0b : r0a;
;         const int cw = min(max(16 * j - 8, 0), 32), qcol = 16 * j + (q & 15), c0 = min(max(qcol - 8, 0), 48);
;         const int nst = nband + 8;
;         const int kb_lat = b * SEQ + r0a * 64 + cw, kb_ctx = MLAT + b * CTX;
;         const bf16_t* kbase = Kp + (size_t)h * 1024 + (size_t)(sig >> 3) * 32768 + (sig & 7) * 16 + 8 * hh;
;         const bf16_t* vbase = Vt + (size_t)h * 1024 + (size_t)hh * 32768 + q * 8;
.LBB0_141:
	s_and_b64 vcc, exec, s[24:25]
	s_cbranch_vccz .LBB0_202
	v_mov_b32_e32 v0, v195
	v_readlane_b32 s5, v251, 6
	v_readfirstlane_b32 s4, v0
	s_ashr_i32 s4, s4, 6
	s_add_i32 s14, s4, s5
	v_readlane_b32 s5, v251, 51
	s_cmp_ge_i32 s14, s5
	s_cbranch_scc1 .LBB0_201
	v_readlane_b32 s12, v250, 1
	v_readlane_b32 s13, v250, 2
	s_add_u32 s6, s12, 0x9600000
	s_addc_u32 s7, s13, 0
	v_lshlrev_b32_e32 v1, 1, v0
	v_and_b32_e32 v2, 19, v0
	s_add_u32 s28, s12, 0x12600000
	v_and_or_b32 v1, v1, 8, v2
	v_lshrrev_b32_e32 v3, 1, v0
	s_addc_u32 s29, s13, 0
	v_and_or_b32 v4, v3, 4, v2
	v_lshlrev_b32_e32 v1, 13, v1
	v_and_b32_e32 v228, 31, v0
	v_writelane_b32 v250, s6, 6
	s_add_u32 s30, s12, 0x1b600000
	v_and_b32_e32 v96, 0x30000, v1
	v_lshlrev_b32_e32 v1, 5, v4
	v_writelane_b32 v250, s7, 7
	s_addc_u32 s31, s13, 0
	s_lshl_b32 s6, s4, 11
	v_bfe_u32 v5, v0, 5, 1
	v_cmp_gt_u32_e64 s[4:5], 16, v228
	v_lshl_add_u64 v[2:3], s[12:13], 0, v[96:97]
	v_and_b32_e32 v96, 0xe0, v1
	v_writelane_b32 v250, s4, 8
	v_lshl_add_u64 v[2:3], v[2:3], 0, v[96:97]
	v_lshlrev_b32_e32 v96, 4, v5
	v_writelane_b32 v250, s5, 9
	v_lshl_add_u64 v[2:3], v[2:3], 0, v[96:97]
	s_mov_b64 s[4:5], 0xde00000
	v_lshlrev_b32_e32 v96, 16, v5
	v_lshl_add_u64 v[198:199], v[2:3], 0, s[4:5]
	v_lshl_add_u64 v[2:3], s[12:13], 0, v[96:97]
	v_lshlrev_b32_e32 v96, 4, v228
	v_lshl_add_u64 v[2:3], v[2:3], 0, v[96:97]
	s_mov_b64 s[4:5], 0x16e00000
	v_lshl_add_u64 v[200:201], v[2:3], 0, s[4:5]
	s_add_i32 s4, s6, 64
	s_lshl_b64 s[0:1], s[0:1], 2
	v_readlane_b32 s6, v251, 62
	v_readlane_b32 s7, v251, 63
	s_add_u32 s0, s0, s6
	v_readlane_b32 s36, v251, 13
	s_addc_u32 s1, s1, s7
	v_readlane_b32 s38, v251, 15
	v_and_b32_e32 v227, 63, v0
	v_readlane_b32 s39, v251, 16
	s_add_u32 s0, s38, s0
	v_bfe_u32 v229, v0, 4, 1
	v_and_b32_e32 v230, 15, v0
	v_lshl_add_u32 v232, v227, 2, s4
	s_addc_u32 s1, s39, s1
	v_and_b32_e32 v0, 32, v0
	s_addk_i32 s4, 0x3a0
	v_lshlrev_b32_e32 v196, 3, v5
	v_lshlrev_b32_e32 v202, 2, v5
	v_or_b32_e32 v231, 0xffffffc0, v227
	v_writelane_b32 v250, s0, 10
	v_add_u32_e32 v233, s4, v0
	v_readlane_b32 s37, v251, 14
	v_readlane_b32 s40, v251, 17
	v_readlane_b32 s41, v251, 18
	v_readlane_b32 s42, v251, 19
	v_readlane_b32 s43, v251, 20
	v_writelane_b32 v250, s1, 11
	v_writelane_b32 v255, -1, 43
	v_and_b32_e32 v0, 19, v228
	v_lshrrev_b32_e32 v1, 1, v228
	v_and_b32_e32 v1, 4, v1
	v_lshlrev_b32_e32 v2, 1, v228
	v_and_b32_e32 v2, 8, v2
	v_or3_b32 v0, v0, v1, v2
	v_lshrrev_b32_e32 v1, 3, v0
	v_and_b32_e32 v2, 7, v0
	v_lshlrev_b32_e32 v1, 11, v1
	v_lshl_add_u32 v1, v2, 5, v1
	v_lshl_add_u32 v241, v196, 1, v1
	v_lshlrev_b32_e32 v2, 8, v196
	v_lshl_add_u32 v2, v228, 4, v2
	v_add_u32_e32 v242, 0x4000, v2
	v_readlane_b32 s4, v252, 0
	v_readlane_b32 s5, v252, 1
	v_readlane_b32 s0, v250, 3
	s_add_u32 s4, s4, 0xde00000
	s_addc_u32 s5, s5, 0
	s_lshl_b32 s1, s0, 16
	v_lshl_add_u32 v96, v227, 4, s1
	v_lshl_add_u64 v[244:245], s[4:5], 0, v[96:97]
	s_add_u32 s4, s4, 0x9000000
	s_addc_u32 s5, s5, 0
	v_lshl_add_u64 v[246:247], s[4:5], 0, v[96:97]
	s_lshl_b32 s1, s0, 11
	s_add_i32 s1, s1, 0x4000
	v_writelane_b32 v255, s1, 42

; #define LDS_WAIT() asm volatile("s_waitcnt lgkmcnt(0)" ::: "memory")
; __device__ __forceinline__ void attn_phase(const Args& a, int layer, LAS unsigned char* lds, int G, int need_ctx) {
;     ...
;         bf16x8 qf[8];
; #pragma unroll
;         for (int c = 0; c < 8; ++c) qf[c] = *(const bf16x8*)(Q + (size_t)qtok * DI + h * 128 + 16 * c + 8 * hh);
;         if (lat) {
;             LDS_WAIT();
;             for (int e = lane; e < 465; e += 64) rp[e] = rpb[h * 465 + e];
;             LDS_WAIT();
;         }
;         const int r0a = min(max(r - 4, 0), 24), r0b = min(max(r - 3, 0), 24), nband = lat ? (r0b + 8 - r0a) : 0;
;         const int qr = r + (q >> 4), myr0 = (q >> 4) ? r0b : r0a;
;         const int cw = min(max(16 * j - 8, 0), 32), qcol = 16 * j + (q & 15), c0 = min(max(qcol - 8, 0), 48);
;         const int nst = nband + 8;
;         const int kb_lat = b * SEQ + r0a * 64 + cw, kb_ctx = MLAT + b * CTX;
;         const bf16_t* kbase = Kp + (size_t)h * 1024 + (size_t)(sig >> 3) * 32768 + (sig & 7) * 16 + 8 * hh;
;         const bf16_t* vbase = Vt + (size_t)h * 1024 + (size_t)hh * 32768 + q * 8;
;         float m_run = -1e30f, l_run = 0.f;
;         f32x16 OT[4];
; #pragma unroll
;         for (int d = 0; d < 4; ++d)
; #pragma unroll
;             for (int t = 0; t < 16; ++t) OT[d][t] = 0.f;
;         bf16x8 kreg[8], vreg[8];
;         { const int kb0 = nband ? kb_lat : kb_ctx;
; #pragma unroll
;           for (int c = 0; c < 8; ++c) kreg[c] = *(const bf16x8*)(kbase + (size_t)(kb0 >> 3) * 32768 + 128 * c); }
.LBB0_148:
	v_ashrrev_i32_e32 v205, 31, v204
	v_readlane_b32 s4, v250, 6
	s_and_b32 s36, s15, 31
	v_lshlrev_b64 v[0:1], 13, v[204:205]
	v_readlane_b32 s5, v250, 7
	s_lshl_b32 s94, s36, 8
	v_lshlrev_b32_e32 v96, 1, v196
	v_lshl_add_u64 v[0:1], s[4:5], 0, v[0:1]
	v_lshl_add_u64 v[0:1], v[0:1], 0, s[94:95]
	v_lshl_add_u64 v[0:1], v[0:1], 0, v[96:97]
	global_load_dwordx4 v[98:101], v[0:1], off
	global_load_dwordx4 v[102:105], v[0:1], off offset:32
	global_load_dwordx4 v[106:109], v[0:1], off offset:64
	global_load_dwordx4 v[110:113], v[0:1], off offset:96
	global_load_dwordx4 v[114:117], v[0:1], off offset:128
	global_load_dwordx4 v[118:121], v[0:1], off offset:160
	global_load_dwordx4 v[122:125], v[0:1], off offset:192
	global_load_dwordx4 v[126:129], v[0:1], off offset:224
	s_andn2_b64 vcc, exec, s[0:1]
	s_cbranch_vccnz .LBB0_152
	v_readlane_b32 s4, v255, 43
	s_cmp_eq_u32 s36, s4
	s_cbranch_scc1 .LBB0_152
	v_writelane_b32 v255, s36, 43
	s_mul_i32 s4, s36, 0x1d1
	s_waitcnt lgkmcnt(0)
	v_add_lshl_u32 v96, v227, s4, 2
	v_readlane_b32 s4, v250, 10
	v_readlane_b32 s5, v250, 11
	s_nop 1
	v_lshl_add_u64 v[0:1], s[4:5], 0, v[96:97]
	global_load_dword v2, v[0:1], off
	global_load_dword v3, v[0:1], off offset:256
	global_load_dword v4, v[0:1], off offset:512
	global_load_dword v5, v[0:1], off offset:768
	global_load_dword v6, v[0:1], off offset:1024
	global_load_dword v7, v[0:1], off offset:1280
	global_load_dword v8, v[0:1], off offset:1536
	v_cmp_gt_u32_e32 vcc, 17, v227
	s_and_saveexec_b64 s[4:5], vcc
	global_load_dword v9, v[0:1], off offset:1792
	s_mov_b64 exec, s[4:5]
	s_waitcnt vmcnt(0)
	ds_write_b32 v232, v2
	ds_write_b32 v232, v3 offset:256
	ds_write_b32 v232, v4 offset:512
	ds_write_b32 v232, v5 offset:768
	ds_write_b32 v232, v6 offset:1024
	ds_write_b32 v232, v7 offset:1280
	ds_write_b32 v232, v8 offset:1536
	s_and_saveexec_b64 s[4:5], vcc
	ds_write_b32 v232, v9 offset:1792
	s_mov_b64 exec, s[4:5]
	s_waitcnt lgkmcnt(0)
.LBB0_152:
	v_sub_u32_e64 v0, s6, 4 clamp
	v_mov_b32_e32 v15, 0
	v_readfirstlane_b32 s4, v0
	v_sub_u32_e64 v0, s6, 3 clamp
	s_min_u32 s37, s4, 24
	v_readfirstlane_b32 s4, v0
	s_min_u32 s4, s4, 24
	s_sub_i32 s5, s4, s37
	s_add_i32 s5, s5, 8
	s_andn2_b32 s100, s6, 2
	s_sub_i32 s100, s100, 4
	s_max_i32 s100, s100, 0
	s_min_i32 s100, s100, 24
	s_mov_b32 vcc_lo, s37
	s_mov_b32 s37, s100
	s_sub_i32 s100, vcc_lo, s100
	s_and_b64 s[0:1], s[0:1], exec
	s_cselect_b32 s15, s5, 0
	s_cmp_lt_i32 s15, -7
	v_mov_b32_e32 v14, v15
	v_mov_b32_e32 v13, v15
	v_mov_b32_e32 v12, v15
	v_mov_b32_e32 v11, v15
	v_mov_b32_e32 v10, v15
	v_mov_b32_e32 v9, v15
	v_mov_b32_e32 v8, v15
	v_mov_b32_e32 v7, v15
	v_mov_b32_e32 v6, v15
	v_mov_b32_e32 v5, v15
	v_mov_b32_e32 v4, v15
	v_mov_b32_e32 v3, v15
	v_mov_b32_e32 v2, v15
	v_mov_b32_e32 v1, v15
	v_mov_b32_e32 v0, v15
	v_mov_b32_e32 v31, v15
	v_mov_b32_e32 v30, v15
	v_mov_b32_e32 v29, v15
	v_mov_b32_e32 v28, v15
	v_mov_b32_e32 v27, v15
	v_mov_b32_e32 v26, v15
	v_mov_b32_e32 v25, v15
	v_mov_b32_e32 v24, v15
	v_mov_b32_e32 v23, v15
	v_mov_b32_e32 v22, v15
	v_mov_b32_e32 v21, v15
	v_mov_b32_e32 v20, v15
	v_mov_b32_e32 v19, v15
	v_mov_b32_e32 v18, v15
	v_mov_b32_e32 v17, v15
	v_mov_b32_e32 v16, v15
	v_mov_b32_e32 v47, v15
	v_mov_b32_e32 v46, v15
	v_mov_b32_e32 v45, v15
	v_mov_b32_e32 v44, v15
	v_mov_b32_e32 v43, v15
	v_mov_b32_e32 v42, v15
	v_mov_b32_e32 v41, v15
	v_mov_b32_e32 v40, v15
	v_mov_b32_e32 v39, v15
	v_mov_b32_e32 v38, v15
	v_mov_b32_e32 v37, v15
	v_mov_b32_e32 v36, v15
	v_mov_b32_e32 v35, v15
	v_mov_b32_e32 v34, v15
	v_mov_b32_e32 v33, v15
	v_mov_b32_e32 v32, v15
	v_mov_b32_e32 v63, v15
	v_mov_b32_e32 v62, v15
	v_mov_b32_e32 v61, v15
	v_mov_b32_e32 v60, v15
	v_mov_b32_e32 v59, v15
	v_mov_b32_e32 v58, v15
	v_mov_b32_e32 v57, v15
	v_mov_b32_e32 v56, v15
	v_mov_b32_e32 v55, v15
	v_mov_b32_e32 v54, v15
	v_mov_b32_e32 v53, v15
	v_mov_b32_e32 v52, v15
	v_mov_b32_e32 v51, v15
	v_mov_b32_e32 v50, v15
	v_mov_b32_e32 v49, v15
	v_mov_b32_e32 v48, v15
	v_mov_b32_e32 v64, v15
	s_cbranch_scc1 .LBB0_199
	v_sub_u32_e64 v0, s7, 8 clamp
	s_lshl_b32 s0, s23, 11
	s_lshl_b32 s1, s37, 6
	v_readfirstlane_b32 s5, v0
	s_or_b32 s0, s1, s0
	s_lshl_b32 s1, s23, 8
	s_min_u32 s12, s5, 32
	s_or_b32 s24, s0, s12
	s_add_i32 s13, s1, 0x2000
	s_or_b32 s26, s6, 2
	s_sub_i32 s26, s26, 3
	s_max_i32 s26, s26, 0
	s_min_i32 s26, s26, 24
	s_add_i32 s26, s26, 8
	s_sub_i32 s26, s26, s37
	s_cmp_lg_u32 s15, 0
	s_cselect_b32 s26, s26, 0
	v_writelane_b32 v255, s26, 44
	s_lshl_b32 s27, s36, 11
	s_lshl_b32 s101, s23, 24
	s_add_i32 s101, s101, s27
	s_lshl_b32 s5, s37, 19
	s_add_i32 s101, s101, s5
	s_lshl_b32 s5, s23, 21
	s_add_i32 s5, s5, s27
	s_add_i32 s5, s5, 0x4000000
	v_writelane_b32 v255, s5, 41
	s_lshl_b32 s24, s12, 8
	v_readlane_b32 s0, v250, 8
	v_mov_b32_e32 v0, s4
	s_add_i32 s1, s37, s100
	v_mov_b32_e32 v2, s1
	v_readlane_b32 s1, v250, 9
	s_lshl_b32 s94, s36, 11
	s_add_i32 s25, s15, 8
	v_cndmask_b32_e64 v96, v0, v2, s[0:1]
	s_mov_b32 s1, s95
	v_writelane_b32 v250, s0, 12
	v_or_b32_e32 v1, s7, v230
	v_writelane_b32 v250, s1, 13
	v_max_i32_e32 v0, 8, v1
	v_add_u32_e32 v0, -8, v0
	v_min_u32_e32 v2, 48, v0
	v_xor_b32_e32 v3, 32, v210
	v_cmp_lt_i32_e32 vcc, v3, v212
	v_add_u32_e32 v0, s12, v196
	v_add_u32_e32 v1, 16, v2
	v_cndmask_b32_e32 v3, v210, v3, vcc
	v_lshlrev_b32_e32 v235, 2, v3
	v_or_b32_e32 v3, 1, v0
	v_cmp_ge_u32_e64 s[40:41], v3, v2
	v_cmp_lt_u32_e64 s[42:43], v3, v1
	v_or_b32_e32 v3, 2, v0
	v_cmp_ge_u32_e64 s[44:45], v3, v2
	v_cmp_lt_u32_e64 s[46:47], v3, v1
	v_or_b32_e32 v3, 3, v0
	v_cmp_ge_u32_e64 s[48:49], v3, v2
	v_cmp_lt_u32_e64 s[50:51], v3, v1
	v_or_b32_e32 v3, 4, v0
	v_cmp_ge_u32_e64 s[52:53], v3, v2
	v_cmp_lt_u32_e64 s[54:55], v3, v1
; __device__ __forceinline__ void attn_phase(const Args& a, int layer, LAS unsigned char* lds, int G, int need_ctx) {
;     ...
;         const int r0a = min(max(r - 4, 0), 24), r0b = min(max(r - 3, 0), 24), nband = lat ? (r0b + 8 - r0a) : 0;
;         const int qr = r + (q >> 4), myr0 = (q >> 4) ? r0b : r0a;
;         const int cw = min(max(16 * j - 8, 0), 32), qcol = 16 * j + (q & 15), c0 = min(max(qcol - 8, 0), 48);
;         const int nst = nband + 8;
;         const int kb_lat = b * SEQ + r0a * 64 + cw, kb_ctx = MLAT + b * CTX;
;         const bf16_t* kbase = Kp + (size_t)h * 1024 + (size_t)(sig >> 3) * 32768 + (sig & 7) * 16 + 8 * hh;
;         const bf16_t* vbase = Vt + (size_t)h * 1024 + (size_t)hh * 32768 + q * 8;
;         float m_run = -1e30f, l_run = 0.f;
;         f32x16 OT[4];
; #pragma unroll
;         for (int d = 0; d < 4; ++d)
; #pragma unroll
;             for (int t = 0; t < 16; ++t) OT[d][t] = 0.f;
;         bf16x8 kreg[8], vreg[8];
;         { const int kb0 = nband ? kb_lat : kb_ctx;
; #pragma unroll
;           for (int c = 0; c < 8; ++c) kreg[c] = *(const bf16x8*)(kbase + (size_t)(kb0 >> 3) * 32768 + 128 * c); }
;         for (int st = 0; st < nst; ++st) {
;             const bool isl = st < nband;
;             const int keybase = isl ? kb_lat + st * 64 : kb_ctx + 32 * (st - nband);
; #pragma unroll
;             for (int d = 0; d < 4; ++d)
; #pragma unroll
;                 for (int s2 = 0; s2 < 2; ++s2) vreg[d * 2 + s2] = *(const bf16x8*)(vbase + (size_t)(keybase >> 3) * 32768 + s2 * 65536 + d * 256);
;             f32x16 sc;
; #pragma unroll
;             for (int t = 0; t < 16; ++t) sc[t] = 0.f;
; #pragma unroll
;             for (int c = 0; c < 8; ++c) sc = __builtin_amdgcn_mfma_f32_32x32x16_bf16(kreg[c], qf[c], sc, 0, 0, 0);
;             if (st + 1 < nst) {
;                 const int kn = (st + 1 < nband) ? kb_lat + (st + 1) * 64 : kb_ctx + 32 * (st + 1 - nband);
; #pragma unroll
;                 for (int c = 0; c < 8; ++c) kreg[c] = *(const bf16x8*)(kbase + (size_t)(kn >> 3) * 32768 + 128 * c);
;             }
;             if (isl) {
;                 const int kr = r0a + st; const bool rowok = (kr >= myr0) && (kr < myr0 + 8);
;                 const int brow = (kr - qr + 7) * 31 - qcol + 15;
; #pragma unroll
;                 for (int t = 0; t < 16; ++t) {
	v_or_b32_e32 v3, 5, v0
	v_cmp_ge_u32_e64 s[56:57], v3, v2
	v_cmp_lt_u32_e64 s[58:59], v3, v1
	v_or_b32_e32 v3, 6, v0
	v_cmp_ge_u32_e64 s[60:61], v3, v2
	v_cmp_lt_u32_e64 s[62:63], v3, v1
	v_or_b32_e32 v3, 7, v0
	v_cmp_ge_u32_e64 s[64:65], v3, v2
	v_cmp_lt_u32_e64 s[66:67], v3, v1
	v_add_u32_e32 v3, 16, v0
	v_cmp_ge_u32_e64 s[68:69], v3, v2
	v_add_u32_e32 v3, 17, v0
	v_cmp_ge_u32_e64 s[72:73], v3, v2
	v_cmp_lt_u32_e64 s[74:75], v3, v1
	v_add_u32_e32 v3, 18, v0
	v_cmp_ge_u32_e64 s[76:77], v3, v2
	v_cmp_lt_u32_e64 s[78:79], v3, v1
	v_add_u32_e32 v3, 19, v0
	v_cmp_ge_u32_e64 s[82:83], v3, v2
	v_cmp_lt_u32_e64 s[84:85], v3, v1
	v_add_u32_e32 v3, 20, v0
	v_cmp_ge_u32_e64 s[86:87], v3, v2
	v_cmp_lt_u32_e64 s[88:89], v3, v1
	v_add_u32_e32 v3, 21, v0
	v_cmp_ge_u32_e64 s[0:1], v0, v2
	v_cmp_lt_u32_e64 s[38:39], v0, v1
	v_cmp_lt_u32_e64 s[70:71], v0, v2
	v_cmp_ge_u32_e64 s[90:91], v3, v2
	v_cmp_lt_u32_e64 s[92:93], v3, v1
	v_add_u32_e32 v3, 22, v0
	v_add_u32_e32 v0, 23, v0
	v_cmp_lt_u32_e64 s[96:97], v3, v1
	v_cmp_ge_u32_e64 s[98:99], v0, v2
	v_cmp_lt_u32_e64 s[4:5], v0, v1
	s_mul_i32 s23, s37, 31
	v_add_u32_e32 v0, s7, v230
	v_add_u32_e32 v1, s6, v229
	v_sub_u32_e32 v0, s23, v0
	v_mul_u32_u24_e32 v1, 31, v1
	v_sub_u32_e32 v0, v0, v1
	s_lshl_b32 s12, s12, 2
	v_lshlrev_b32_e32 v0, 2, v0
	s_lshl_b32 s6, s15, 5
	v_mov_b32_e32 v237, 0
	s_mov_b32 s27, 0
	v_add_u32_e32 v234, 8, v96
	v_cmp_ge_u32_e64 s[94:95], v3, v2
	v_add3_u32 v236, s12, v0, v233
	v_readlane_b32 s23, v255, 44
	v_mov_b32_e32 v254, 0xff61b1e6
	v_mov_b32_e32 v238, 0xf149f2ca
	v_mov_b32_e32 v48, 0
	v_mov_b32_e32 v49, v237
	v_mov_b32_e32 v50, v237
	v_mov_b32_e32 v51, v237
	v_mov_b32_e32 v52, v237
	v_mov_b32_e32 v53, v237
	v_mov_b32_e32 v54, v237
	v_mov_b32_e32 v55, v237
	v_mov_b32_e32 v56, v237
	v_mov_b32_e32 v57, v237
	v_mov_b32_e32 v58, v237
	v_mov_b32_e32 v59, v237
	v_mov_b32_e32 v60, v237
	v_mov_b32_e32 v61, v237
	v_mov_b32_e32 v62, v237
	v_mov_b32_e32 v63, v237
	v_mov_b32_e32 v32, 0
	v_mov_b32_e32 v33, v237
	v_mov_b32_e32 v34, v237
	v_mov_b32_e32 v35, v237
	v_mov_b32_e32 v36, v237
	v_mov_b32_e32 v37, v237
	v_mov_b32_e32 v38, v237
	v_mov_b32_e32 v39, v237
	v_mov_b32_e32 v40, v237
	v_mov_b32_e32 v41, v237
	v_mov_b32_e32 v42, v237
	v_mov_b32_e32 v43, v237
	v_mov_b32_e32 v44, v237
	v_mov_b32_e32 v45, v237
	v_mov_b32_e32 v46, v237
	v_mov_b32_e32 v47, v237
	v_mov_b32_e32 v16, 0
	v_mov_b32_e32 v17, v237
	v_mov_b32_e32 v18, v237
	v_mov_b32_e32 v19, v237
	v_mov_b32_e32 v20, v237
	v_mov_b32_e32 v21, v237
	v_mov_b32_e32 v22, v237
	v_mov_b32_e32 v23, v237
	v_mov_b32_e32 v24, v237
	v_mov_b32_e32 v25, v237
	v_mov_b32_e32 v26, v237
	v_mov_b32_e32 v27, v237
	v_mov_b32_e32 v28, v237
	v_mov_b32_e32 v29, v237
	v_mov_b32_e32 v30, v237
	v_mov_b32_e32 v31, v237
	v_mov_b32_e32 v0, 0
	v_mov_b32_e32 v1, v237
	v_mov_b32_e32 v2, v237
	v_mov_b32_e32 v3, v237
	v_mov_b32_e32 v4, v237
	v_mov_b32_e32 v5, v237
	v_mov_b32_e32 v6, v237
	v_mov_b32_e32 v7, v237
	v_mov_b32_e32 v8, v237
	v_mov_b32_e32 v9, v237
	v_mov_b32_e32 v10, v237
	v_mov_b32_e32 v11, v237
	v_mov_b32_e32 v12, v237
	v_mov_b32_e32 v13, v237
	v_mov_b32_e32 v14, v237
	v_mov_b32_e32 v15, v237
	s_add_i32 s25, s23, 4
	s_mov_b32 s27, 0
	s_barrier
	s_cmp_lt_u32 s27, s23
	s_cbranch_scc0 .Latt_cxa
	s_lshl_b32 s12, s27, 19
	s_add_i32 s12, s12, s101
	s_branch .Latt_cda
.Latt_cxa:
	v_readlane_b32 s12, v255, 41
	s_sub_i32 s13, s27, s23
	s_lshl_b32 s13, s13, 19
	s_add_i32 s12, s12, s13
.Latt_cda:
	s_mov_b32 s13, 0
	v_lshl_add_u64 v[206:207], v[244:245], 0, s[12:13]
	v_lshl_add_u64 v[208:209], v[246:247], 0, s[12:13]
	v_readlane_b32 s13, v255, 42
	s_and_b32 s12, s27, 1
	s_lshl_b32 s12, s12, 15
	s_add_i32 s13, s13, s12
	s_mov_b32 m0, s13
	s_nop 0
	global_load_lds_dwordx4 v[206:207], off
	global_load_lds_dwordx4 v[206:207], off offset:1024
	s_add_i32 m0, s13, 0x4000
	s_nop 0
	global_load_lds_dwordx4 v[208:209], off
	global_load_lds_dwordx4 v[208:209], off offset:1024
.Latt_slot:
	s_waitcnt vmcnt(0)
	s_waitcnt lgkmcnt(0)
	s_barrier
	s_add_i32 s26, s27, 1
	s_cmp_ge_u32 s26, s25
	s_cbranch_scc1 .Latt_nodma
	s_cmp_lt_u32 s26, s23
	s_cbranch_scc0 .Latt_cxb
	s_lshl_b32 s12, s26, 19
	s_add_i32 s12, s12, s101
	s_branch .Latt_cdb
.Latt_cxb:
	v_readlane_b32 s12, v255, 41
	s_sub_i32 s13, s26, s23
	s_lshl_b32 s13, s13, 19
	s_add_i32 s12, s12, s13
.Latt_cdb:
	s_mov_b32 s13, 0
	v_lshl_add_u64 v[206:207], v[244:245], 0, s[12:13]
	v_lshl_add_u64 v[208:209], v[246:247], 0, s[12:13]
	v_readlane_b32 s13, v255, 42
	s_and_b32 s12, s26, 1
	s_lshl_b32 s12, s12, 15
	s_add_i32 s13, s13, s12
	s_mov_b32 m0, s13
	s_nop 0
	global_load_lds_dwordx4 v[206:207], off
	global_load_lds_dwordx4 v[206:207], off offset:1024
	s_add_i32 m0, s13, 0x4000
	s_nop 0
	global_load_lds_dwordx4 v[208:209], off
	global_load_lds_dwordx4 v[208:209], off offset:1024
.Latt_nodma:
	s_and_b32 s12, s27, 1
	s_lshl_b32 s12, s12, 15
	s_add_i32 s12, s12, 0x4000
	s_cmp_lt_u32 s27, s23
	s_cbranch_scc0 .Latt_ctxslot
	s_sub_i32 s13, s27, s100
	s_cmp_lt_u32 s13, s15
	s_cbranch_scc0 .Latt_slot_next
	s_mov_b64 s[6:7], -1
	s_mov_b32 s26, 1
	s_add_i32 s12, s12, s24
	s_branch .Latt_step
.Latt_ctxslot:
	s_mov_b64 s[6:7], 0
	s_mov_b32 s26, 2
; __device__ __forceinline__ void attn_phase(const Args& a, int layer, LAS unsigned char* lds, int G, int need_ctx) {
;     ...
;         for (int st = 0; st < nst; ++st) {
;             const bool isl = st < nband;
;             const int keybase = isl ? kb_lat + st * 64 : kb_ctx + 32 * (st - nband);
; #pragma unroll
;             for (int d = 0; d < 4; ++d)
; #pragma unroll
;                 for (int s2 = 0; s2 < 2; ++s2) vreg[d * 2 + s2] = *(const bf16x8*)(vbase + (size_t)(keybase >> 3) * 32768 + s2 * 65536 + d * 256);
;             f32x16 sc;
; #pragma unroll
;             for (int t = 0; t < 16; ++t) sc[t] = 0.f;
; #pragma unroll
;             for (int c = 0; c < 8; ++c) sc = __builtin_amdgcn_mfma_f32_32x32x16_bf16(kreg[c], qf[c], sc, 0, 0, 0);
;             if (st + 1 < nst) {
;                 const int kn = (st + 1 < nband) ? kb_lat + (st + 1) * 64 : kb_ctx + 32 * (st + 1 - nband);
; #pragma unroll
;                 for (int c = 0; c < 8; ++c) kreg[c] = *(const bf16x8*)(kbase + (size_t)(kn >> 3) * 32768 + 128 * c);
;             }
;             if (isl) {
;                 const int kr = r0a + st; const bool rowok = (kr >= myr0) && (kr < myr0 + 8);
;                 const int brow = (kr - qr + 7) * 31 - qcol + 15;
; #pragma unroll
;                 for (int t = 0; t < 16; ++t) {
;                     const int kc = cw + 16 * (t >> 3) + 8 * hh + (t & 7); const bool valid = rowok && (kc >= c0) && (kc < c0 + 16);
;                     const float bias = rp[valid ? (brow + kc) : 0];
;                     sc[t] = valid ? sc[t] + bias : -3.0e38f;
;                 }
;             }
.Latt_step:
	v_add_u32_e32 v243, s12, v241
	v_add_u32_e32 v248, s12, v242
	ds_read_b128 v[146:149], v243
	ds_read_b128 v[150:153], v243 offset:256
	ds_read_b128 v[154:157], v243 offset:512
	ds_read_b128 v[158:161], v243 offset:768
	ds_read_b128 v[142:145], v243 offset:1024
	ds_read_b128 v[138:141], v243 offset:1280
	ds_read_b128 v[134:137], v243 offset:1536
	ds_read_b128 v[130:133], v243 offset:1792
	ds_read_b128 v[190:193], v248
	ds_read_b128 v[186:189], v248 offset:4096
	ds_read_b128 v[182:185], v248 offset:512
	ds_read_b128 v[178:181], v248 offset:4608
	ds_read_b128 v[174:177], v248 offset:1024
	ds_read_b128 v[170:173], v248 offset:5120
	ds_read_b128 v[166:169], v248 offset:1536
	ds_read_b128 v[162:165], v248 offset:5632
	s_waitcnt lgkmcnt(8)
	v_mfma_f32_32x32x16_bf16 v[64:79], v[146:149], v[98:101], 0
	v_mfma_f32_32x32x16_bf16 v[64:79], v[150:153], v[102:105], v[64:79]
	v_mfma_f32_32x32x16_bf16 v[64:79], v[154:157], v[106:109], v[64:79]
	v_mfma_f32_32x32x16_bf16 v[64:79], v[158:161], v[110:113], v[64:79]
	v_mfma_f32_32x32x16_bf16 v[64:79], v[142:145], v[114:117], v[64:79]
	v_mfma_f32_32x32x16_bf16 v[64:79], v[138:141], v[118:121], v[64:79]
	v_mfma_f32_32x32x16_bf16 v[64:79], v[134:137], v[122:125], v[64:79]
	v_mfma_f32_32x32x16_bf16 v[64:79], v[130:133], v[126:129], v[64:79]
	s_andn2_b64 vcc, exec, s[6:7]
	s_cbranch_vccnz .LBB0_196
	s_add_i32 s12, s37, s27
	v_cmp_ge_u32_e64 s[6:7], s12, v96
	v_cmp_lt_u32_e32 vcc, s12, v234
	s_and_b64 s[6:7], s[6:7], vcc
	v_cndmask_b32_e64 v253, v232, v236, s[6:7]
	ds_read2_b32 v[80:81], v253 offset0:0 offset1:1
	ds_read2_b32 v[82:83], v253 offset0:2 offset1:3
	ds_read2_b32 v[84:85], v253 offset0:4 offset1:5
	ds_read2_b32 v[86:87], v253 offset0:6 offset1:7
	ds_read2_b32 v[88:89], v253 offset0:16 offset1:17
	ds_read2_b32 v[90:91], v253 offset0:18 offset1:19
	ds_read2_b32 v[92:93], v253 offset0:20 offset1:21
	ds_read2_b32 v[94:95], v253 offset0:22 offset1:23
	s_and_b64 vcc, s[6:7], s[0:1]
	s_and_b64 vcc, vcc, s[38:39]
	s_waitcnt lgkmcnt(7)
	v_add_f32_e32 v80, v64, v80
	v_cndmask_b32_e32 v64, v254, v80, vcc
	s_and_b64 s[12:13], s[6:7], s[40:41]
	s_and_b64 s[12:13], s[12:13], s[42:43]
	v_add_f32_e32 v81, v65, v81
	v_cndmask_b32_e64 v65, v254, v81, s[12:13]
	s_and_b64 vcc, s[6:7], s[44:45]
	s_and_b64 vcc, vcc, s[46:47]
	s_waitcnt lgkmcnt(6)
	v_add_f32_e32 v82, v66, v82
	v_cndmask_b32_e32 v66, v254, v82, vcc
	s_and_b64 s[12:13], s[6:7], s[48:49]
	s_and_b64 s[12:13], s[12:13], s[50:51]
	v_add_f32_e32 v83, v67, v83
	v_cndmask_b32_e64 v67, v254, v83, s[12:13]
	s_and_b64 vcc, s[6:7], s[52:53]
	s_and_b64 vcc, vcc, s[54:55]
	s_waitcnt lgkmcnt(5)
	v_add_f32_e32 v84, v68, v84
	v_cndmask_b32_e32 v68, v254, v84, vcc
	s_and_b64 s[12:13], s[6:7], s[56:57]
	s_and_b64 s[12:13], s[12:13], s[58:59]
	v_add_f32_e32 v85, v69, v85
	v_cndmask_b32_e64 v69, v254, v85, s[12:13]
	s_and_b64 vcc, s[6:7], s[60:61]
	s_and_b64 vcc, vcc, s[62:63]
	s_waitcnt lgkmcnt(4)
	v_add_f32_e32 v86, v70, v86
	v_cndmask_b32_e32 v70, v254, v86, vcc
	s_and_b64 s[12:13], s[6:7], s[64:65]
	s_and_b64 s[12:13], s[12:13], s[66:67]
	v_add_f32_e32 v87, v71, v87
	v_cndmask_b32_e64 v71, v254, v87, s[12:13]
	s_and_b64 vcc, s[6:7], s[68:69]
	s_and_b64 vcc, vcc, s[70:71]
	s_waitcnt lgkmcnt(3)
	v_add_f32_e32 v88, v72, v88
	v_cndmask_b32_e32 v72, v254, v88, vcc
	s_and_b64 s[12:13], s[6:7], s[72:73]
	s_and_b64 s[12:13], s[12:13], s[74:75]
	v_add_f32_e32 v89, v73, v89
	v_cndmask_b32_e64 v73, v254, v89, s[12:13]
	s_and_b64 vcc, s[6:7], s[76:77]
	s_and_b64 vcc, vcc, s[78:79]
	s_waitcnt lgkmcnt(2)
	v_add_f32_e32 v90, v74, v90
	v_cndmask_b32_e32 v74, v254, v90, vcc
	s_and_b64 s[12:13], s[6:7], s[82:83]
	s_and_b64 s[12:13], s[12:13], s[84:85]
	v_add_f32_e32 v91, v75, v91
	v_cndmask_b32_e64 v75, v254, v91, s[12:13]
	s_and_b64 vcc, s[6:7], s[86:87]
	s_and_b64 vcc, vcc, s[88:89]
	s_waitcnt lgkmcnt(1)
	v_add_f32_e32 v92, v76, v92
	v_cndmask_b32_e32 v76, v254, v92, vcc
	s_and_b64 s[12:13], s[6:7], s[90:91]
	s_and_b64 s[12:13], s[12:13], s[92:93]
	v_add_f32_e32 v93, v77, v93
	v_cndmask_b32_e64 v77, v254, v93, s[12:13]
	s_and_b64 vcc, s[6:7], s[94:95]
	s_and_b64 vcc, vcc, s[96:97]
	s_waitcnt lgkmcnt(0)
	v_add_f32_e32 v94, v78, v94
	v_cndmask_b32_e32 v78, v254, v94, vcc
	s_and_b64 s[12:13], s[6:7], s[98:99]
	s_and_b64 s[12:13], s[12:13], s[4:5]
	v_add_f32_e32 v95, v79, v95
	v_cndmask_b32_e64 v79, v254, v95, s[12:13]
; __device__ __forceinline__ void attn_phase(const Args& a, int layer, LAS unsigned char* lds, int G, int need_ctx) {
;     ...
;             float mx = sc[0];
; #pragma unroll
;             for (int t = 1; t < 16; ++t) mx = fmaxf(mx, sc[t]);
;             mx = fmaxf(mx, __shfl_xor(mx, 32));
;             const float m_new = fmaxf(m_run, mx), alpha = __expf(m_run - m_new);
;             float rs = 0.f;
; #pragma unroll
;             for (int t = 0; t < 16; ++t) { sc[t] = __expf(sc[t] - m_new); rs += sc[t]; }
;             rs += __shfl_xor(rs, 32);
;             l_run = l_run * alpha + rs; m_run = m_new;
;             union { u32x4 u; bf16x8 v; } P0, P1;
;             P0.u.x = pk2(sc[0], sc[1]); P0.u.y = pk2(sc[2], sc[3]); P0.u.z = pk2(sc[4], sc[5]); P0.u.w = pk2(sc[6], sc[7]);
;             P1.u.x = pk2(sc[8], sc[9]); P1.u.y = pk2(sc[10], sc[11]); P1.u.z = pk2(sc[12], sc[13]); P1.u.w = pk2(sc[14], sc[15]);
; #pragma unroll
;             for (int d = 0; d < 4; ++d) {
; #pragma unroll
;                 for (int t = 0; t < 16; ++t) OT[d][t] *= alpha;
;                 OT[d] = __builtin_amdgcn_mfma_f32_32x32x16_bf16(vreg[d * 2 + 0], P0.v, OT[d], 0, 0, 0);
;                 OT[d] = __builtin_amdgcn_mfma_f32_32x32x16_bf16(vreg[d * 2 + 1], P1.v, OT[d], 0, 0, 0);
;             }
;         }
.LBB0_196:
	s_nop 8
	v_max_f32_e32 v80, v65, v65
	v_max_f32_e32 v81, v64, v64
	v_max_f32_e32 v80, v81, v80
	v_max3_f32 v80, v80, v66, v67
	v_max3_f32 v80, v80, v68, v69
	v_max3_f32 v80, v80, v70, v71
	v_max3_f32 v80, v80, v72, v73
	v_max3_f32 v80, v80, v74, v75
	v_max3_f32 v80, v80, v76, v77
	v_max3_f32 v80, v80, v78, v79
	ds_bpermute_b32 v81, v235, v80
	s_waitcnt lgkmcnt(0)
	v_max3_f32 v80, v238, v80, v81
	v_sub_f32_e32 v64, v64, v80
	v_mul_f32_e32 v64, 0x3fb8aa3b, v64
	v_sub_f32_e32 v65, v65, v80
	v_exp_f32_e32 v64, v64
	v_mul_f32_e32 v65, 0x3fb8aa3b, v65
	v_sub_f32_e32 v66, v66, v80
	v_exp_f32_e32 v65, v65
	v_mul_f32_e32 v66, 0x3fb8aa3b, v66
	v_sub_f32_e32 v67, v67, v80
	v_exp_f32_e32 v66, v66
	v_mul_f32_e32 v67, 0x3fb8aa3b, v67
	v_sub_f32_e32 v68, v68, v80
	v_exp_f32_e32 v67, v67
	v_mul_f32_e32 v68, 0x3fb8aa3b, v68
	v_add_f32_e32 v82, 0, v64
	v_exp_f32_e32 v83, v68
	v_add_f32_e32 v82, v65, v82
	v_add_f32_e32 v82, v66, v82
	v_sub_f32_e32 v69, v69, v80
	v_add_f32_e32 v82, v67, v82
	v_mul_f32_e32 v69, 0x3fb8aa3b, v69
	v_add_f32_e32 v68, v83, v82
	v_exp_f32_e32 v82, v69
	v_sub_f32_e32 v69, v70, v80
	v_mul_f32_e32 v69, 0x3fb8aa3b, v69
	v_exp_f32_e32 v84, v69
	v_sub_f32_e32 v69, v71, v80
	v_mul_f32_e32 v69, 0x3fb8aa3b, v69
	v_exp_f32_e32 v71, v69
	v_sub_f32_e32 v69, v72, v80
	v_mul_f32_e32 v69, 0x3fb8aa3b, v69
	v_exp_f32_e32 v85, v69
	v_sub_f32_e32 v69, v73, v80
	v_mul_f32_e32 v69, 0x3fb8aa3b, v69
	v_exp_f32_e32 v73, v69
	v_sub_f32_e32 v69, v74, v80
	v_mul_f32_e32 v69, 0x3fb8aa3b, v69
	v_exp_f32_e32 v74, v69
	v_sub_f32_e32 v69, v75, v80
	v_mul_f32_e32 v69, 0x3fb8aa3b, v69
	v_exp_f32_e32 v75, v69
	v_sub_f32_e32 v69, v76, v80
	v_mul_f32_e32 v69, 0x3fb8aa3b, v69
	v_add_f32_e32 v68, v82, v68
	v_exp_f32_e32 v76, v69
	v_sub_f32_e32 v69, v77, v80
	v_add_f32_e32 v68, v84, v68
	v_mul_f32_e32 v69, 0x3fb8aa3b, v69
	v_add_f32_e32 v68, v71, v68
	v_exp_f32_e32 v77, v69
	v_sub_f32_e32 v69, v78, v80
	v_add_f32_e32 v68, v85, v68
	v_mul_f32_e32 v69, 0x3fb8aa3b, v69
	v_sub_f32_e32 v81, v238, v80
	v_add_f32_e32 v68, v73, v68
	v_exp_f32_e32 v78, v69
	v_sub_f32_e32 v69, v79, v80
	v_mul_f32_e32 v81, 0x3fb8aa3b, v81
	v_add_f32_e32 v68, v74, v68
	v_mul_f32_e32 v69, 0x3fb8aa3b, v69
	v_add_f32_e32 v68, v75, v68
	v_exp_f32_e32 v79, v69
	v_exp_f32_e32 v72, v81
	v_add_f32_e32 v68, v76, v68
	v_add_f32_e32 v68, v77, v68
	v_add_f32_e32 v68, v78, v68
	v_add_f32_e32 v86, v79, v68
	v_cvt_pk_bf16_f32 v68, v64, v65
	v_cvt_pk_bf16_f32 v69, v66, v67
	v_cvt_pk_bf16_f32 v70, v83, v82
	v_cvt_pk_bf16_f32 v71, v84, v71
	v_pk_mul_f32 v[62:63], v[62:63], v[72:73] op_sel_hi:[1,0]
	v_pk_mul_f32 v[60:61], v[60:61], v[72:73] op_sel_hi:[1,0]
	v_pk_mul_f32 v[58:59], v[58:59], v[72:73] op_sel_hi:[1,0]
	v_pk_mul_f32 v[56:57], v[56:57], v[72:73] op_sel_hi:[1,0]
	v_pk_mul_f32 v[54:55], v[54:55], v[72:73] op_sel_hi:[1,0]
	v_pk_mul_f32 v[52:53], v[52:53], v[72:73] op_sel_hi:[1,0]
	v_pk_mul_f32 v[50:51], v[50:51], v[72:73] op_sel_hi:[1,0]
	v_pk_mul_f32 v[48:49], v[48:49], v[72:73] op_sel_hi:[1,0]
	v_pk_mul_f32 v[46:47], v[46:47], v[72:73] op_sel_hi:[1,0]
	v_pk_mul_f32 v[44:45], v[44:45], v[72:73] op_sel_hi:[1,0]
	v_pk_mul_f32 v[42:43], v[42:43], v[72:73] op_sel_hi:[1,0]
	v_pk_mul_f32 v[40:41], v[40:41], v[72:73] op_sel_hi:[1,0]
	v_pk_mul_f32 v[38:39], v[38:39], v[72:73] op_sel_hi:[1,0]
	v_pk_mul_f32 v[36:37], v[36:37], v[72:73] op_sel_hi:[1,0]
	v_pk_mul_f32 v[34:35], v[34:35], v[72:73] op_sel_hi:[1,0]
	v_pk_mul_f32 v[32:33], v[32:33], v[72:73] op_sel_hi:[1,0]
	v_pk_mul_f32 v[30:31], v[30:31], v[72:73] op_sel_hi:[1,0]
	v_pk_mul_f32 v[28:29], v[28:29], v[72:73] op_sel_hi:[1,0]
	v_pk_mul_f32 v[26:27], v[26:27], v[72:73] op_sel_hi:[1,0]
	v_pk_mul_f32 v[24:25], v[24:25], v[72:73] op_sel_hi:[1,0]
	v_pk_mul_f32 v[22:23], v[22:23], v[72:73] op_sel_hi:[1,0]
	v_pk_mul_f32 v[20:21], v[20:21], v[72:73] op_sel_hi:[1,0]
	v_pk_mul_f32 v[18:19], v[18:19], v[72:73] op_sel_hi:[1,0]
	v_pk_mul_f32 v[16:17], v[16:17], v[72:73] op_sel_hi:[1,0]
	v_pk_mul_f32 v[14:15], v[14:15], v[72:73] op_sel_hi:[1,0]
	v_pk_mul_f32 v[12:13], v[12:13], v[72:73] op_sel_hi:[1,0]
	v_pk_mul_f32 v[10:11], v[10:11], v[72:73] op_sel_hi:[1,0]
	v_pk_mul_f32 v[8:9], v[8:9], v[72:73] op_sel_hi:[1,0]
	v_pk_mul_f32 v[6:7], v[6:7], v[72:73] op_sel_hi:[1,0]
	v_pk_mul_f32 v[4:5], v[4:5], v[72:73] op_sel_hi:[1,0]
	v_pk_mul_f32 v[2:3], v[2:3], v[72:73] op_sel_hi:[1,0]
	v_pk_mul_f32 v[0:1], v[0:1], v[72:73] op_sel_hi:[1,0]
	v_mfma_f32_32x32x16_bf16 v[48:63], v[190:193], v[68:71], v[48:63]
	v_cvt_pk_bf16_f32 v64, v85, v73
	v_cvt_pk_bf16_f32 v65, v74, v75
	v_cvt_pk_bf16_f32 v66, v76, v77
	v_cvt_pk_bf16_f32 v67, v78, v79
	ds_bpermute_b32 v81, v235, v86
	v_mfma_f32_32x32x16_bf16 v[32:47], v[182:185], v[68:71], v[32:47]
	v_mfma_f32_32x32x16_bf16 v[16:31], v[174:177], v[68:71], v[16:31]
	v_mfma_f32_32x32x16_bf16 v[0:15], v[166:169], v[68:71], v[0:15]
	v_mfma_f32_32x32x16_bf16 v[48:63], v[186:189], v[64:67], v[48:63]
	v_mfma_f32_32x32x16_bf16 v[32:47], v[178:181], v[64:67], v[32:47]
	v_mfma_f32_32x32x16_bf16 v[16:31], v[170:173], v[64:67], v[16:31]
	v_mfma_f32_32x32x16_bf16 v[0:15], v[162:165], v[64:67], v[0:15]
	s_waitcnt lgkmcnt(0)
	v_add_f32_e32 v64, v86, v81
	v_fmac_f32_e32 v64, v237, v72
	v_mov_b32_e32 v238, v80
	v_mov_b32_e32 v237, v64
	s_sub_i32 s26, s26, 1
	s_cmp_eq_u32 s26, 0
	s_cbranch_scc1 .Latt_slot_next
	s_and_b32 s12, s27, 1
	s_lshl_b32 s12, s12, 15
	s_add_i32 s12, s12, 0x6000
	s_mov_b64 s[6:7], 0
	s_branch .Latt_step
.Latt_slot_next:
	s_cmp_lt_u32 s27, s23
	s_cbranch_scc0 .Latt_noadv
	v_add_u32_e32 v236, 0x7c, v236
.Latt_noadv:
	s_add_i32 s27, s27, 1
	s_cmp_lt_u32 s27, s25
	s_cbranch_scc1 .Latt_slot
